# P9 final rmsnorm loop hand-written with a contiguous-per-instruction lane mapping (lane owns 4 consecutive elements of each 256-element piece): every f32 store instruction writes 1 KiB of whole lines
# speedup vs baseline: 1.0069x; 1.0050x over previous
; __device__ __forceinline__ int lane_id_() { int l; asm volatile("v_mbcnt_lo_u32_b32 %0, -1, 0\n\tv_mbcnt_hi_u32_b32 %0, -1, %0" : "=v"(l)); return l; }
; __global__ void __launch_bounds__(512) mega(Params p) {
;     ...
;     { const int wid = WID, lane = lane_id_(); const float* fn = p.in[16]; const float* ssq = (const float*)(ws + WS_SSQ3); const bf16_t* h3b = (const bf16_t*)(ws + WS_ACT);
;       for (int r = bx * 8 + wid; r < MTOK; r += G * 8) { float* xr = p.out + (size_t)r * DM; const bf16_t* hr = h3b + (size_t)r * DM;
;           u32x4 hv[4];
; #pragma unroll
;           for (int i = 0; i < 4; ++i) hv[i] = *(const u32x4*)(hr + i * 512 + lane * 8);
;           float s = (lane < 32) ? ssq[(size_t)r * 32 + lane] : 0.f;
.LBB0_1080:
	v_readlane_b32 s0, v254, 1
	v_readlane_b32 s1, v254, 2
	s_and_b64 vcc, exec, s[0:1]
	s_waitcnt lgkmcnt(0)
	s_barrier
	v_mbcnt_lo_u32_b32 v0, -1, 0
	v_mbcnt_hi_u32_b32 v0, -1, v0
	s_cbranch_vccz .LBB0_1085
	v_and_b32_e32 v4, 64, v209
	v_add_u32_e32 v6, 64, v4
	v_xor_b32_e32 v7, 32, v209
	v_cmp_lt_i32_e32 vcc, v7, v6
	v_lshlrev_b32_e32 v2, 3, v0
	v_ashrrev_i32_e32 v3, 31, v2
	v_cndmask_b32_e32 v7, v209, v7, vcc
	v_lshlrev_b32_e32 v28, 2, v7
	v_xor_b32_e32 v7, 16, v209
	v_cmp_lt_i32_e32 vcc, v7, v6
	v_lshlrev_b64 v[4:5], 2, v[2:3]
	v_lshl_add_u64 v[16:17], s[88:89], 0, v[4:5]
	v_cndmask_b32_e32 v7, v209, v7, vcc
	v_lshlrev_b32_e32 v29, 2, v7
	v_xor_b32_e32 v7, 8, v209
	v_cmp_lt_i32_e32 vcc, v7, v6
	s_mov_b64 s[2:3], 0x1800
	s_ashr_i32 s19, s18, 31
	v_cndmask_b32_e32 v7, v209, v7, vcc
	v_lshlrev_b32_e32 v30, 2, v7
	v_xor_b32_e32 v7, 4, v209
	v_cmp_lt_i32_e32 vcc, v7, v6
	v_ashrrev_i32_e32 v1, 31, v0
	v_lshl_add_u64 v[20:21], v[16:17], 0, s[2:3]
	v_cndmask_b32_e32 v7, v209, v7, vcc
	v_lshlrev_b32_e32 v31, 2, v7
	v_xor_b32_e32 v7, 2, v209
	s_lshl_b64 s[2:3], s[18:19], 7
	v_cmp_gt_i32_e64 s[0:1], 32, v0
	v_cmp_lt_i32_e32 vcc, v7, v6
	v_lshl_add_u64 v[0:1], v[0:1], 2, s[2:3]
	s_mov_b64 s[2:3], 0x1d400000
	s_ashr_i32 s21, s20, 31
	s_lshl_b64 s[4:5], s[18:19], 12
	v_cndmask_b32_e32 v7, v209, v7, vcc
	v_lshl_add_u64 v[22:23], v[0:1], 0, s[2:3]
	s_lshl_b64 s[2:3], s[20:21], 7
	v_lshl_add_u64 v[24:25], v[2:3], 1, s[4:5]
	s_lshl_b64 s[4:5], s[20:21], 12
	s_lshl_b64 s[8:9], s[18:19], 13
	v_lshlrev_b32_e32 v32, 2, v7
	v_xor_b32_e32 v7, 1, v209
	s_add_u32 s8, s90, s8
	v_cmp_lt_i32_e32 vcc, v7, v6
	s_addc_u32 s9, s91, s9
	s_mov_b64 s[6:7], 0x1000
	v_cndmask_b32_e32 v6, v209, v7, vcc
	v_lshl_add_u64 v[0:1], s[8:9], 0, v[4:5]
	v_lshlrev_b32_e32 v33, 2, v6
	v_lshl_add_u64 v[18:19], v[16:17], 0, s[6:7]
	v_lshl_add_u64 v[26:27], v[0:1], 0, s[6:7]
	s_lshl_b64 s[6:7], s[20:21], 13
	v_mov_b32_e32 v34, 0x358637bd
	s_mov_b32 s10, 0x800000
	v_lshlrev_b32_e32 v100, 3, v209
	v_lshlrev_b32_e32 v101, 4, v209
	s_lshl_b64 s[12:13], s[18:19], 12
	s_add_u32 s12, s12, s94
	s_addc_u32 s13, s13, s95
	s_add_u32 s12, s12, 0xef00000
	s_addc_u32 s13, s13, 0
	s_lshl_b64 s[14:15], s[18:19], 13
	s_add_u32 s14, s14, s90
	s_addc_u32 s15, s15, s91
	s_add_u32 s16, s14, 0x1000
	s_addc_u32 s17, s15, 0
	s_add_u32 s22, s88, 0x1000
	s_addc_u32 s23, s89, 0
	global_load_dwordx4 v[60:63], v101, s[88:89]
	global_load_dwordx4 v[64:67], v101, s[88:89] offset:1024
	global_load_dwordx4 v[68:71], v101, s[88:89] offset:2048
	global_load_dwordx4 v[72:75], v101, s[88:89] offset:3072
	global_load_dwordx4 v[76:79], v101, s[22:23]
	global_load_dwordx4 v[80:83], v101, s[22:23] offset:1024
	global_load_dwordx4 v[84:87], v101, s[22:23] offset:2048
	global_load_dwordx4 v[88:91], v101, s[22:23] offset:3072
	s_cmpk_gt_i32 s18, 0x3fff
	s_cbranch_scc1 .LBB0_1085
; __device__ __forceinline__ float bflo(unsigned w) { return __uint_as_float(w << 16); }
; __device__ __forceinline__ float bfhi(unsigned w) { return __uint_as_float(w & 0xffff0000u); }
; __global__ void __launch_bounds__(512) mega(Params p) {
;     ...
;       for (int r = bx * 8 + wid; r < MTOK; r += G * 8) { float* xr = p.out + (size_t)r * DM; const bf16_t* hr = h3b + (size_t)r * DM;
;           u32x4 hv[4];
; #pragma unroll
;           for (int i = 0; i < 4; ++i) hv[i] = *(const u32x4*)(hr + i * 512 + lane * 8);
;           float s = (lane < 32) ? ssq[(size_t)r * 32 + lane] : 0.f;
; #pragma unroll
;           for (int o = 32; o >= 1; o >>= 1) s += __shfl_xor(s, o);
;           const float rstd = rsqrtf(s * (1.0f / 2048.0f) + EPS);
; #pragma unroll
;           for (int i = 0; i < 4; ++i) { const f32x4 g0 = *(const f32x4*)(fn + i * 512 + lane * 8), g1 = *(const f32x4*)(fn + i * 512 + lane * 8 + 4);
;               f32x4 a, b2; a[0] = bflo(hv[i].x) * rstd * g0[0]; a[1] = bfhi(hv[i].x) * rstd * g0[1]; a[2] = bflo(hv[i].y) * rstd * g0[2]; a[3] = bfhi(hv[i].y) * rstd * g0[3];
;               b2[0] = bflo(hv[i].z) * rstd * g1[0]; b2[1] = bfhi(hv[i].z) * rstd * g1[1]; b2[2] = bflo(hv[i].w) * rstd * g1[2]; b2[3] = bfhi(hv[i].w) * rstd * g1[3];
;               __builtin_nontemporal_store(a, (f32x4*)(xr + i * 512 + lane * 8)); __builtin_nontemporal_store(b2, (f32x4*)(xr + i * 512 + lane * 8 + 4)); } } }
.Lp9n_loop:
	v_mov_b32_e32 v35, 0
	global_load_dwordx2 v[0:1], v100, s[12:13]
	global_load_dwordx2 v[2:3], v100, s[12:13] offset:512
	global_load_dwordx2 v[4:5], v100, s[12:13] offset:1024
	global_load_dwordx2 v[6:7], v100, s[12:13] offset:1536
	global_load_dwordx2 v[8:9], v100, s[12:13] offset:2048
	global_load_dwordx2 v[10:11], v100, s[12:13] offset:2560
	global_load_dwordx2 v[12:13], v100, s[12:13] offset:3072
	global_load_dwordx2 v[14:15], v100, s[12:13] offset:3584
	s_and_saveexec_b64 s[8:9], s[0:1]
	v_lshl_add_u64 v[36:37], s[94:95], 0, v[22:23]
	global_load_dword v35, v[36:37], off
	s_or_b64 exec, exec, s[8:9]
	s_add_i32 s18, s18, s20
	v_lshl_add_u64 v[22:23], v[22:23], 0, s[2:3]
	s_add_u32 s12, s12, s4
	s_addc_u32 s13, s13, s5
	s_waitcnt vmcnt(0)
	ds_bpermute_b32 v44, v28, v35
	s_waitcnt lgkmcnt(0)
	v_add_f32_e32 v35, v35, v44
	ds_bpermute_b32 v44, v29, v35
	s_waitcnt lgkmcnt(0)
	v_add_f32_e32 v35, v35, v44
	ds_bpermute_b32 v44, v30, v35
	s_waitcnt lgkmcnt(0)
	v_add_f32_e32 v35, v35, v44
	ds_bpermute_b32 v44, v31, v35
	s_waitcnt lgkmcnt(0)
	v_add_f32_e32 v35, v35, v44
	ds_bpermute_b32 v45, v32, v35
	s_waitcnt lgkmcnt(0)
	v_add_f32_e32 v35, v35, v45
	ds_bpermute_b32 v47, v33, v35
	s_waitcnt lgkmcnt(0)
	v_add_f32_e32 v35, v35, v47
	v_fmamk_f32 v35, v35, 0x3a000000, v34
	v_mul_f32_e32 v47, 0x4b800000, v35
	v_cmp_gt_f32_e32 vcc, s10, v35
	s_nop 1
	v_cndmask_b32_e32 v35, v35, v47, vcc
	v_rsq_f32_e32 v35, v35
	s_nop 0
	v_mul_f32_e32 v48, 0x45800000, v35
	v_cndmask_b32_e32 v48, v35, v48, vcc
	v_lshlrev_b32_e32 v40, 16, v0
	v_and_b32_e32 v41, 0xffff0000, v0
	v_lshlrev_b32_e32 v42, 16, v1
	v_and_b32_e32 v43, 0xffff0000, v1
	v_pk_mul_f32 v[40:41], v[48:49], v[40:41] op_sel_hi:[0,1]
	v_pk_mul_f32 v[42:43], v[48:49], v[42:43] op_sel_hi:[0,1]
	v_pk_mul_f32 v[44:45], v[40:41], v[60:61]
	v_pk_mul_f32 v[46:47], v[42:43], v[62:63]
	global_store_dwordx4 v101, v[44:47], s[14:15] nt
	v_lshlrev_b32_e32 v50, 16, v2
	v_and_b32_e32 v51, 0xffff0000, v2
	v_lshlrev_b32_e32 v52, 16, v3
	v_and_b32_e32 v53, 0xffff0000, v3
	v_pk_mul_f32 v[50:51], v[48:49], v[50:51] op_sel_hi:[0,1]
	v_pk_mul_f32 v[52:53], v[48:49], v[52:53] op_sel_hi:[0,1]
	v_pk_mul_f32 v[54:55], v[50:51], v[64:65]
	v_pk_mul_f32 v[56:57], v[52:53], v[66:67]
	global_store_dwordx4 v101, v[54:57], s[14:15] offset:1024 nt
	v_lshlrev_b32_e32 v40, 16, v4
	v_and_b32_e32 v41, 0xffff0000, v4
	v_lshlrev_b32_e32 v42, 16, v5
	v_and_b32_e32 v43, 0xffff0000, v5
	v_pk_mul_f32 v[40:41], v[48:49], v[40:41] op_sel_hi:[0,1]
	v_pk_mul_f32 v[42:43], v[48:49], v[42:43] op_sel_hi:[0,1]
	v_pk_mul_f32 v[44:45], v[40:41], v[68:69]
	v_pk_mul_f32 v[46:47], v[42:43], v[70:71]
	global_store_dwordx4 v101, v[44:47], s[14:15] offset:2048 nt
	v_lshlrev_b32_e32 v50, 16, v6
	v_and_b32_e32 v51, 0xffff0000, v6
	v_lshlrev_b32_e32 v52, 16, v7
	v_and_b32_e32 v53, 0xffff0000, v7
	v_pk_mul_f32 v[50:51], v[48:49], v[50:51] op_sel_hi:[0,1]
	v_pk_mul_f32 v[52:53], v[48:49], v[52:53] op_sel_hi:[0,1]
	v_pk_mul_f32 v[54:55], v[50:51], v[72:73]
	v_pk_mul_f32 v[56:57], v[52:53], v[74:75]
	global_store_dwordx4 v101, v[54:57], s[14:15] offset:3072 nt
	v_lshlrev_b32_e32 v40, 16, v8
	v_and_b32_e32 v41, 0xffff0000, v8
	v_lshlrev_b32_e32 v42, 16, v9
	v_and_b32_e32 v43, 0xffff0000, v9
	v_pk_mul_f32 v[40:41], v[48:49], v[40:41] op_sel_hi:[0,1]
	v_pk_mul_f32 v[42:43], v[48:49], v[42:43] op_sel_hi:[0,1]
	v_pk_mul_f32 v[44:45], v[40:41], v[76:77]
	v_pk_mul_f32 v[46:47], v[42:43], v[78:79]
	global_store_dwordx4 v101, v[44:47], s[16:17] nt
	v_lshlrev_b32_e32 v50, 16, v10
	v_and_b32_e32 v51, 0xffff0000, v10
	v_lshlrev_b32_e32 v52, 16, v11
	v_and_b32_e32 v53, 0xffff0000, v11
	v_pk_mul_f32 v[50:51], v[48:49], v[50:51] op_sel_hi:[0,1]
	v_pk_mul_f32 v[52:53], v[48:49], v[52:53] op_sel_hi:[0,1]
	v_pk_mul_f32 v[54:55], v[50:51], v[80:81]
	v_pk_mul_f32 v[56:57], v[52:53], v[82:83]
	global_store_dwordx4 v101, v[54:57], s[16:17] offset:1024 nt
	v_lshlrev_b32_e32 v40, 16, v12
	v_and_b32_e32 v41, 0xffff0000, v12
	v_lshlrev_b32_e32 v42, 16, v13
	v_and_b32_e32 v43, 0xffff0000, v13
	v_pk_mul_f32 v[40:41], v[48:49], v[40:41] op_sel_hi:[0,1]
	v_pk_mul_f32 v[42:43], v[48:49], v[42:43] op_sel_hi:[0,1]
	v_pk_mul_f32 v[44:45], v[40:41], v[84:85]
	v_pk_mul_f32 v[46:47], v[42:43], v[86:87]
	global_store_dwordx4 v101, v[44:47], s[16:17] offset:2048 nt
	v_lshlrev_b32_e32 v50, 16, v14
	v_and_b32_e32 v51, 0xffff0000, v14
	v_lshlrev_b32_e32 v52, 16, v15
	v_and_b32_e32 v53, 0xffff0000, v15
	v_pk_mul_f32 v[50:51], v[48:49], v[50:51] op_sel_hi:[0,1]
	v_pk_mul_f32 v[52:53], v[48:49], v[52:53] op_sel_hi:[0,1]
	v_pk_mul_f32 v[54:55], v[50:51], v[88:89]
	v_pk_mul_f32 v[56:57], v[52:53], v[90:91]
	global_store_dwordx4 v101, v[54:57], s[16:17] offset:3072 nt
	s_add_u32 s14, s14, s6
	s_addc_u32 s15, s15, s7
	s_add_u32 s16, s16, s6
	s_addc_u32 s17, s17, s7
	s_cmpk_gt_i32 s18, 0x3fff
	s_cbranch_scc0 .Lp9n_loop
